# selected-block attention: token ranges of the four XCDs of a kv group sized 4608/4352/3840/3584 (later ranges select from more blocks)
# baseline (speedup 1.0000x reference)
.LBB0_841:
	s_andn2_b64 vcc, exec, s[0:1]
	v_readlane_b32 s3, v254, 47
	s_cbranch_vccnz .LBB0_934
	s_mov_b64 s[22:23], exec
	s_and_b32 s2, s3, 1
	s_lshr_b32 s0, s3, 1
	s_and_b32 s0, s0, 3
	s_mul_i32 s26, s0, 0x1200
	s_cmp_eq_u32 s0, 2
	s_cselect_b32 s27, 0x100, 0
	s_sub_i32 s26, s26, s27
	s_cmp_eq_u32 s0, 3
	s_cselect_b32 s27, 0x400, 0
	s_sub_i32 s26, s26, s27
	s_mul_i32 s27, s0, 0x100
	s_sub_i32 s27, 0x1200, s27
	s_cmp_eq_u32 s0, 2
	s_cselect_b32 s2, 0x100, 0
	s_sub_i32 s27, s27, s2
	s_cmp_eq_u32 s0, 3
	s_cselect_b32 s2, 0x100, 0
	s_sub_i32 s27, s27, s2
	s_add_i32 s27, s26, s27
	s_and_b32 s2, s3, 1
	v_readfirstlane_b32 s1, v220
	s_and_b32 s0, s3, -8
	s_add_i32 s0, s0, s1
	s_add_i32 s26, s26, s0
	s_lshl_b32 s0, s2, 6
	s_add_u32 s12, s12, s0
	s_addc_u32 s13, s13, 0
	s_lshl_b32 s0, s2, 21
	s_add_u32 s18, s18, s0
	s_addc_u32 s19, s19, 0
	s_add_u32 s16, s16, s0
	s_addc_u32 s17, s17, 0
	v_lshl_or_b32 v202, s2, 3, v200
	v_and_b32_e32 v140, 63, v208
	v_lshlrev_b32_e32 v140, 4, v140
	v_add_u32_e32 v141, 0x1000, v140
	s_mov_b32 s48, 0x3e38aa3b
	s_mov_b32 s49, 0x3e38aa3b
	s_mov_b32 s57, 0x20400
	v_mov_b32_e32 v179, 0xf149f2ca
	v_lshl_add_u32 v66, v202, 2, s57
	ds_read_b32 v178, v66 offset:1984
	s_barrier
	s_and_b32 s0, s1, 3
	s_lshl_b32 s0, s0, 11
	s_cmp_lt_u32 s1, 4
	s_cselect_b32 s40, s18, s16
	s_cselect_b32 s41, s19, s17
	s_cselect_b32 s2, 0, 0x2000
	s_add_u32 s40, s40, s0
	s_addc_u32 s41, s41, 0
	s_add_i32 s2, s2, s0
	s_mov_b32 m0, s2
	s_nop 0
	global_load_lds_dwordx4 v140, s[40:41]
	s_add_u32 s40, s40, 0x400
	s_addc_u32 s41, s41, 0
	s_add_i32 m0, s2, 0x400
	s_nop 0
	global_load_lds_dwordx4 v140, s[40:41]
	s_waitcnt vmcnt(0)
	s_barrier
	s_lshl_b32 s0, s26, 7
	s_add_u32 s38, s12, s0
	s_addc_u32 s39, s13, 0
	v_lshrrev_b32_e32 v144, 3, v199
	global_load_dword v176, v144, s[38:39]
	s_lshl_b32 s0, s26, 11
	s_add_u32 s54, s14, s0
	s_addc_u32 s55, s15, 0
	v_lshlrev_b32_e32 v67, 7, v202
	v_lshl_add_u32 v67, v198, 1, v67
	global_load_dwordx4 v[16:19], v67, s[54:55]
	global_load_dwordx4 v[20:23], v67, s[54:55] offset:64
	s_mov_b64 s[34:35], s[18:19]
	s_mov_b64 s[36:37], s[16:17]
	ds_read_b128 v[32:35], v140 offset:0
	ds_read_b128 v[36:39], v140 offset:1024
	ds_read_b128 v[40:43], v140 offset:2048
	ds_read_b128 v[44:47], v140 offset:3072
	ds_read_b128 v[48:51], v140 offset:4096
	ds_read_b128 v[52:55], v140 offset:5120
	ds_read_b128 v[56:59], v140 offset:6144
	ds_read_b128 v[60:63], v140 offset:7168
	ds_read_b128 v[100:103], v140 offset:8192
	ds_read_b128 v[104:107], v140 offset:9216
	ds_read_b128 v[108:111], v140 offset:10240
	ds_read_b128 v[112:115], v140 offset:11264
	ds_read_b128 v[116:119], v140 offset:12288
	ds_read_b128 v[120:123], v140 offset:13312
	ds_read_b128 v[124:127], v140 offset:14336
	ds_read_b128 v[128:131], v140 offset:15360
	s_lshr_b32 s0, s26, 6
	s_add_i32 s0, s0, 1
	s_min_i32 s28, s0, 16
	s_mov_b32 s29, 0
	s_mov_b32 s30, 0
	s_mov_b32 s51, 0
	v_mov_b32_e32 v196, 0xf149f2ca
	v_mov_b32_e32 v197, 0
	v_mov_b32_e32 v0, 0
	v_mov_b32_e32 v1, 0
	v_mov_b32_e32 v2, 0
	v_mov_b32_e32 v3, 0
	v_mov_b32_e32 v4, 0
	v_mov_b32_e32 v5, 0
	v_mov_b32_e32 v6, 0
	v_mov_b32_e32 v7, 0
	v_mov_b32_e32 v8, 0
	v_mov_b32_e32 v9, 0
	v_mov_b32_e32 v10, 0
	v_mov_b32_e32 v11, 0
	v_mov_b32_e32 v12, 0
	v_mov_b32_e32 v13, 0
	v_mov_b32_e32 v14, 0
	v_mov_b32_e32 v15, 0
	s_waitcnt lgkmcnt(0)
	v_mul_f32_e32 v178, 0x3fb8aa3b, v178
	s_waitcnt vmcnt(2)
